# FFN-down to mixer seam: XCD leader skips the L2 writeback when placement is canonical (all consumers of that seam are XCD-local)
# speedup vs baseline: 1.0049x; 1.0049x over previous
; __device__ __forceinline__ unsigned xb_add(unsigned* p, unsigned v) { return __hip_atomic_fetch_add(p, v, __ATOMIC_RELAXED, __HIP_MEMORY_SCOPE_AGENT); }
; __device__ __forceinline__ void xcd_barrier(const XcdBarrier& b) {
;     ...
;         if (old + 1u == (gen + 1u) * nloc) {
;             __builtin_amdgcn_fence(__ATOMIC_RELEASE, "agent");
;             asm volatile("s_waitcnt vmcnt(0)" ::: "memory");
;             const unsigned og = xb_add(&bar[XB_TOP], 1u);
;             const unsigned tg = og / nx;
;             if (og + 1u == (tg + 1u) * nx) xb_add(&bar[XB_TOPGEN], 1u);
.LBB0_366:
	s_andn2_saveexec_b64 s[10:11], s[10:11]
	s_cbranch_execz .LBB0_386
	s_mov_b64 s[12:13], exec
	v_mov_b32_e32 v6, 0x21008
	ds_read_b32 v6, v6
	s_waitcnt lgkmcnt(0)
	v_readfirstlane_b32 s30, v6
	s_cmp_eq_u32 s30, 1
	s_cbranch_scc1 .Lxb2_nowb
	buffer_wbl2 sc1
.Lxb2_nowb:
	s_waitcnt lgkmcnt(0)
	s_waitcnt vmcnt(0)
	v_mbcnt_lo_u32_b32 v1, s12, 0
	v_mbcnt_hi_u32_b32 v1, s13, v1
	v_cmp_eq_u32_e32 vcc, 0, v1
	s_and_saveexec_b64 s[14:15], vcc
	s_cbranch_execz .LBB0_369
	s_bcnt1_i32_b64 s2, s[12:13]
	v_mov_b32_e32 v2, s2
	v_mov_b32_e32 v3, 0x9783000
	global_atomic_add v2, v3, v2, s[6:7] offset:1024 sc0
